# GEMM unit switch: accumulators zeroed with 64 v_mov_b64 instead of 128 v_mov_b32
# speedup vs baseline: 1.0094x; 1.0017x over previous
; template <class Epi, class Sched, bool ALIGN_EPI = false, bool SP2 = false>
; __device__ __forceinline__ void gemm_phase(PG8_LAS unsigned char* lds, const Gemm g, const Sched& S, const Epi& E) {
;     ...
;         const bool has_next = S.next(ui + 1, nxt);
;         const char* nA = has_next ? (const char*)g.A + (size_t)nxt.pm * tstep : cA; const char* nB = has_next ? (const char*)g.Bt + (size_t)nxt.pn * tstep : cB;
;         for (int t = 0; t < nt; t += 2) {
;             const bool last = (t == nt - 2);
;             const char* a1 = cA + (size_t)(t + 1) * kstep;
;             const char* a2 = last ? nA : cA + (size_t)(t + 2) * kstep; const char* b2 = last ? nB : cB + (size_t)(t + 2) * kstep;
;             const char* a3 = a2 + kstep; const char* b3 = b2 + kstep;
;             if (last && has_next) S.a_ready(nxt);
;     ...
;         for (int a = 0; a < 2; ++a)
; #pragma unroll
;             for (int b = 0; b < 2; ++b)
; #pragma unroll
;                 for (int m = 0; m < 4; ++m)
; #pragma unroll
;                     for (int n = 0; n < 2; ++n) acc[a][b][m][n] = (f32x4){0.f, 0.f, 0.f, 0.f};
.LBB0_181:
	s_ashr_i32 s55, s54, 31
	s_lshl_b64 s[56:57], s[54:55], 20
	s_add_u32 s56, s5, s56
	s_addc_u32 s57, s61, s57
	s_and_b64 s[62:63], s[2:3], exec
	s_cselect_b32 s55, s57, s67
	s_cselect_b32 s94, s56, s66
	s_ashr_i32 s53, s52, 31
	s_lshl_b64 s[62:63], s[52:53], 20
	s_add_u32 s62, s71, s62
	s_addc_u32 s63, s72, s63
	s_and_b64 s[68:69], s[2:3], exec
	s_cselect_b32 s53, s63, s65
	s_cselect_b32 s95, s62, s64
	s_lshl_b32 s68, s54, 8
	s_ashr_i32 s69, s68, 31
	s_add_u32 s96, s64, 0x100
	s_addc_u32 s97, s65, 0
	s_add_u32 s64, s66, 0x80080
	v_mov_b32_e32 v2, 0
	s_waitcnt lgkmcnt(0)
	v_lshl_add_u64 v[156:157], s[68:69], 2, v[136:137]
	s_addc_u32 s65, s67, 0
	s_mov_b32 s98, -2
	v_mov_b64_e32 v[2:3], 0
	v_mov_b64_e32 v[4:5], 0
	v_mov_b64_e32 v[6:7], 0
	v_mov_b64_e32 v[8:9], 0
	v_mov_b64_e32 v[10:11], 0
	v_mov_b64_e32 v[12:13], 0
	v_mov_b64_e32 v[14:15], 0
	v_mov_b64_e32 v[16:17], 0
	v_mov_b64_e32 v[18:19], 0
	v_mov_b64_e32 v[20:21], 0
	v_mov_b64_e32 v[22:23], 0
	v_mov_b64_e32 v[24:25], 0
	v_mov_b64_e32 v[26:27], 0
	v_mov_b64_e32 v[28:29], 0
	v_mov_b64_e32 v[30:31], 0
	v_mov_b64_e32 v[32:33], 0
	v_mov_b64_e32 v[34:35], 0
	v_mov_b64_e32 v[36:37], 0
	v_mov_b64_e32 v[38:39], 0
	v_mov_b64_e32 v[40:41], 0
	v_mov_b64_e32 v[42:43], 0
	v_mov_b64_e32 v[44:45], 0
	v_mov_b64_e32 v[46:47], 0
	v_mov_b64_e32 v[48:49], 0
	v_mov_b64_e32 v[50:51], 0
	v_mov_b64_e32 v[52:53], 0
	v_mov_b64_e32 v[54:55], 0
	v_mov_b64_e32 v[56:57], 0
	v_mov_b64_e32 v[58:59], 0
	v_mov_b64_e32 v[60:61], 0
	v_mov_b64_e32 v[62:63], 0
	v_mov_b64_e32 v[64:65], 0
	v_mov_b64_e32 v[66:67], 0
	v_mov_b64_e32 v[68:69], 0
	v_mov_b64_e32 v[70:71], 0
	v_mov_b64_e32 v[72:73], 0
	v_mov_b64_e32 v[74:75], 0
	v_mov_b64_e32 v[76:77], 0
	v_mov_b64_e32 v[78:79], 0
	v_mov_b64_e32 v[80:81], 0
	v_mov_b64_e32 v[82:83], 0
	v_mov_b64_e32 v[84:85], 0
	v_mov_b64_e32 v[86:87], 0
	v_mov_b64_e32 v[88:89], 0
	v_mov_b64_e32 v[90:91], 0
	v_mov_b64_e32 v[92:93], 0
	v_mov_b64_e32 v[94:95], 0
	v_mov_b64_e32 v[96:97], 0
	v_mov_b64_e32 v[98:99], 0
	v_mov_b64_e32 v[100:101], 0
	v_mov_b64_e32 v[102:103], 0
	v_mov_b64_e32 v[104:105], 0
	v_mov_b64_e32 v[106:107], 0
	v_mov_b64_e32 v[108:109], 0
	v_mov_b64_e32 v[110:111], 0
	v_mov_b64_e32 v[112:113], 0
	v_mov_b64_e32 v[114:115], 0
	v_mov_b64_e32 v[116:117], 0
	v_mov_b64_e32 v[118:119], 0
	v_mov_b64_e32 v[120:121], 0
	v_mov_b64_e32 v[122:123], 0
	v_mov_b64_e32 v[124:125], 0
	v_mov_b64_e32 v[126:127], 0
	v_mov_b64_e32 v[128:129], 0
	s_branch .LBB0_183

; template <class Epi, class Sched, bool ALIGN_EPI = false, bool SP2 = false>
; __device__ __forceinline__ void gemm_phase(PG8_LAS unsigned char* lds, const Gemm g, const Sched& S, const Epi& E) {
;     ...
;         const bool has_next = S.next(ui + 1, nxt);
;         const char* nA = has_next ? (const char*)g.A + (size_t)nxt.pm * tstep : cA; const char* nB = has_next ? (const char*)g.Bt + (size_t)nxt.pn * tstep : cB;
;         for (int t = 0; t < nt; t += 2) {
;             const bool last = (t == nt - 2);
;             const char* a1 = cA + (size_t)(t + 1) * kstep;
;             const char* a2 = last ? nA : cA + (size_t)(t + 2) * kstep; const char* b2 = last ? nB : cB + (size_t)(t + 2) * kstep;
;             const char* a3 = a2 + kstep; const char* b3 = b2 + kstep;
;     ...
;         for (int a = 0; a < 2; ++a)
; #pragma unroll
;             for (int b = 0; b < 2; ++b)
; #pragma unroll
;                 for (int m = 0; m < 4; ++m)
; #pragma unroll
;                     for (int n = 0; n < 2; ++n) acc[a][b][m][n] = (f32x4){0.f, 0.f, 0.f, 0.f};
.LBB0_211:
	s_ashr_i32 s57, s56, 31
	s_lshl_b64 s[62:63], s[56:57], 20
	s_add_u32 s62, s79, s62
	s_addc_u32 s63, s80, s63
	s_and_b64 s[64:65], s[2:3], exec
	s_cselect_b32 s57, s63, s71
	s_cselect_b32 s94, s62, s70
	s_ashr_i32 s55, s54, 31
	s_lshl_b64 s[64:65], s[54:55], 20
	s_add_u32 s64, s5, s64
	s_addc_u32 s65, s61, s65
	s_and_b64 s[72:73], s[2:3], exec
	s_cselect_b32 s55, s65, s69
	s_cselect_b32 s95, s64, s68
	s_add_u32 s96, s68, 0x100
	s_addc_u32 s97, s69, 0
	s_add_u32 s68, s70, 0x80080
	v_mov_b32_e32 v2, 0
	s_addc_u32 s69, s71, 0
	s_mov_b32 s98, -2
	v_mov_b64_e32 v[2:3], 0
	v_mov_b64_e32 v[4:5], 0
	v_mov_b64_e32 v[6:7], 0
	v_mov_b64_e32 v[8:9], 0
	v_mov_b64_e32 v[10:11], 0
	v_mov_b64_e32 v[12:13], 0
	v_mov_b64_e32 v[14:15], 0
	v_mov_b64_e32 v[16:17], 0
	v_mov_b64_e32 v[18:19], 0
	v_mov_b64_e32 v[20:21], 0
	v_mov_b64_e32 v[22:23], 0
	v_mov_b64_e32 v[24:25], 0
	v_mov_b64_e32 v[26:27], 0
	v_mov_b64_e32 v[28:29], 0
	v_mov_b64_e32 v[30:31], 0
	v_mov_b64_e32 v[32:33], 0
	v_mov_b64_e32 v[34:35], 0
	v_mov_b64_e32 v[36:37], 0
	v_mov_b64_e32 v[38:39], 0
	v_mov_b64_e32 v[40:41], 0
	v_mov_b64_e32 v[42:43], 0
	v_mov_b64_e32 v[44:45], 0
	v_mov_b64_e32 v[46:47], 0
	v_mov_b64_e32 v[48:49], 0
	v_mov_b64_e32 v[50:51], 0
	v_mov_b64_e32 v[52:53], 0
	v_mov_b64_e32 v[54:55], 0
	v_mov_b64_e32 v[56:57], 0
	v_mov_b64_e32 v[58:59], 0
	v_mov_b64_e32 v[60:61], 0
	v_mov_b64_e32 v[62:63], 0
	v_mov_b64_e32 v[64:65], 0
	v_mov_b64_e32 v[66:67], 0
	v_mov_b64_e32 v[68:69], 0
	v_mov_b64_e32 v[70:71], 0
	v_mov_b64_e32 v[72:73], 0
	v_mov_b64_e32 v[74:75], 0
	v_mov_b64_e32 v[76:77], 0
	v_mov_b64_e32 v[78:79], 0
	v_mov_b64_e32 v[80:81], 0
	v_mov_b64_e32 v[82:83], 0
	v_mov_b64_e32 v[84:85], 0
	v_mov_b64_e32 v[86:87], 0
	v_mov_b64_e32 v[88:89], 0
	v_mov_b64_e32 v[90:91], 0
	v_mov_b64_e32 v[92:93], 0
	v_mov_b64_e32 v[94:95], 0
	v_mov_b64_e32 v[96:97], 0
	v_mov_b64_e32 v[98:99], 0
	v_mov_b64_e32 v[100:101], 0
	v_mov_b64_e32 v[102:103], 0
	v_mov_b64_e32 v[104:105], 0
	v_mov_b64_e32 v[106:107], 0
	v_mov_b64_e32 v[108:109], 0
	v_mov_b64_e32 v[110:111], 0
	v_mov_b64_e32 v[112:113], 0
	v_mov_b64_e32 v[114:115], 0
	v_mov_b64_e32 v[116:117], 0
	v_mov_b64_e32 v[118:119], 0
	v_mov_b64_e32 v[120:121], 0
	v_mov_b64_e32 v[122:123], 0
	v_mov_b64_e32 v[124:125], 0
	v_mov_b64_e32 v[126:127], 0
	v_mov_b64_e32 v[128:129], 0

; template <class Epi, class Sched, bool ALIGN_EPI = false, bool SP2 = false>
; __device__ __forceinline__ void gemm_phase(PG8_LAS unsigned char* lds, const Gemm g, const Sched& S, const Epi& E) {
;     ...
;         const bool has_next = S.next(ui + 1, nxt);
;         const char* nA = has_next ? (const char*)g.A + (size_t)nxt.pm * tstep : cA; const char* nB = has_next ? (const char*)g.Bt + (size_t)nxt.pn * tstep : cB;
;         for (int t = 0; t < nt; t += 2) {
;             const bool last = (t == nt - 2);
;             const char* a1 = cA + (size_t)(t + 1) * kstep;
;             const char* a2 = last ? nA : cA + (size_t)(t + 2) * kstep; const char* b2 = last ? nB : cB + (size_t)(t + 2) * kstep;
;             const char* a3 = a2 + kstep; const char* b3 = b2 + kstep;
;     ...
;         for (int a = 0; a < 2; ++a)
; #pragma unroll
;             for (int b = 0; b < 2; ++b)
; #pragma unroll
;                 for (int m = 0; m < 4; ++m)
; #pragma unroll
;                     for (int n = 0; n < 2; ++n) acc[a][b][m][n] = (f32x4){0.f, 0.f, 0.f, 0.f};
.LBB0_516:
	s_ashr_i32 s43, s42, 31
	s_lshl_b64 s[44:45], s[42:43], 20
	s_add_u32 s44, s61, s44
	s_addc_u32 s45, s62, s45
	s_and_b64 s[46:47], s[6:7], exec
	s_cselect_b32 s13, s45, s53
	s_cselect_b32 s43, s44, s52
	s_ashr_i32 s41, s40, 31
	s_lshl_b64 s[46:47], s[40:41], 20
	s_add_u32 s46, s56, s46
	s_addc_u32 s47, s57, s47
	s_and_b64 s[54:55], s[6:7], exec
	s_cselect_b32 s41, s47, s51
	s_cselect_b32 s49, s46, s50
	s_add_u32 s76, s50, 0x100
	s_addc_u32 s77, s51, 0
	s_add_u32 s50, s52, 0x80080
	v_mov_b32_e32 v2, 0
	s_addc_u32 s51, s53, 0
	s_mov_b32 s78, -2
	s_waitcnt lgkmcnt(0)
	v_mov_b64_e32 v[2:3], 0
	v_mov_b64_e32 v[4:5], 0
	v_mov_b64_e32 v[6:7], 0
	v_mov_b64_e32 v[8:9], 0
	v_mov_b64_e32 v[10:11], 0
	v_mov_b64_e32 v[12:13], 0
	v_mov_b64_e32 v[14:15], 0
	v_mov_b64_e32 v[16:17], 0
	v_mov_b64_e32 v[18:19], 0
	v_mov_b64_e32 v[20:21], 0
	v_mov_b64_e32 v[22:23], 0
	v_mov_b64_e32 v[24:25], 0
	v_mov_b64_e32 v[26:27], 0
	v_mov_b64_e32 v[28:29], 0
	v_mov_b64_e32 v[30:31], 0
	v_mov_b64_e32 v[32:33], 0
	v_mov_b64_e32 v[34:35], 0
	v_mov_b64_e32 v[36:37], 0
	v_mov_b64_e32 v[38:39], 0
	v_mov_b64_e32 v[40:41], 0
	v_mov_b64_e32 v[42:43], 0
	v_mov_b64_e32 v[44:45], 0
	v_mov_b64_e32 v[46:47], 0
	v_mov_b64_e32 v[48:49], 0
	v_mov_b64_e32 v[50:51], 0
	v_mov_b64_e32 v[52:53], 0
	v_mov_b64_e32 v[54:55], 0
	v_mov_b64_e32 v[56:57], 0
	v_mov_b64_e32 v[58:59], 0
	v_mov_b64_e32 v[60:61], 0
	v_mov_b64_e32 v[62:63], 0
	v_mov_b64_e32 v[64:65], 0
	v_mov_b64_e32 v[66:67], 0
	v_mov_b64_e32 v[68:69], 0
	v_mov_b64_e32 v[70:71], 0
	v_mov_b64_e32 v[72:73], 0
	v_mov_b64_e32 v[74:75], 0
	v_mov_b64_e32 v[76:77], 0
	v_mov_b64_e32 v[78:79], 0
	v_mov_b64_e32 v[80:81], 0
	v_mov_b64_e32 v[82:83], 0
	v_mov_b64_e32 v[84:85], 0
	v_mov_b64_e32 v[86:87], 0
	v_mov_b64_e32 v[88:89], 0
	v_mov_b64_e32 v[90:91], 0
	v_mov_b64_e32 v[92:93], 0
	v_mov_b64_e32 v[94:95], 0
	v_mov_b64_e32 v[96:97], 0
	v_mov_b64_e32 v[98:99], 0
	v_mov_b64_e32 v[100:101], 0
	v_mov_b64_e32 v[102:103], 0
	v_mov_b64_e32 v[104:105], 0
	v_mov_b64_e32 v[106:107], 0
	v_mov_b64_e32 v[108:109], 0
	v_mov_b64_e32 v[110:111], 0
	v_mov_b64_e32 v[112:113], 0
	v_mov_b64_e32 v[114:115], 0
	v_mov_b64_e32 v[116:117], 0
	v_mov_b64_e32 v[118:119], 0
	v_mov_b64_e32 v[120:121], 0
	v_mov_b64_e32 v[122:123], 0
	v_mov_b64_e32 v[124:125], 0
	v_mov_b64_e32 v[126:127], 0
	v_mov_b64_e32 v[128:129], 0

; template <class Epi, class Sched, bool ALIGN_EPI = false, bool SP2 = false>
; __device__ __forceinline__ void gemm_phase(PG8_LAS unsigned char* lds, const Gemm g, const Sched& S, const Epi& E) {
;     ...
;         const bool has_next = S.next(ui + 1, nxt);
;         const char* nA = has_next ? (const char*)g.A + (size_t)nxt.pm * tstep : cA; const char* nB = has_next ? (const char*)g.Bt + (size_t)nxt.pn * tstep : cB;
;         for (int t = 0; t < nt; t += 2) {
;             const bool last = (t == nt - 2);
;             const char* a1 = cA + (size_t)(t + 1) * kstep;
;             const char* a2 = last ? nA : cA + (size_t)(t + 2) * kstep; const char* b2 = last ? nB : cB + (size_t)(t + 2) * kstep;
;             const char* a3 = a2 + kstep; const char* b3 = b2 + kstep;
;             if (last && has_next) S.a_ready(nxt);
;     ...
;         for (int a = 0; a < 2; ++a)
; #pragma unroll
;             for (int b = 0; b < 2; ++b)
; #pragma unroll
;                 for (int m = 0; m < 4; ++m)
; #pragma unroll
;                     for (int n = 0; n < 2; ++n) acc[a][b][m][n] = (f32x4){0.f, 0.f, 0.f, 0.f};
.LBB0_691:
	s_ashr_i32 s17, s16, 31
	s_lshl_b64 s[18:19], s[16:17], 20
	s_add_u32 s18, s40, s18
	s_addc_u32 s19, s41, s19
	s_and_b64 s[20:21], s[2:3], exec
	s_cselect_b32 s17, s19, s27
	s_cselect_b32 s60, s18, s26
	s_ashr_i32 s15, s14, 31
	s_lshl_b64 s[20:21], s[14:15], 20
	s_add_u32 s20, s38, s20
	s_addc_u32 s21, s39, s21
	s_and_b64 s[36:37], s[2:3], exec
	s_cselect_b32 s15, s21, s25
	s_cselect_b32 s61, s20, s24
	s_lshl_b32 s36, s16, 8
	s_ashr_i32 s37, s36, 31
	s_add_u32 s62, s24, 0x100
	s_addc_u32 s63, s25, 0
	s_add_u32 s24, s26, 0x80080
	v_mov_b32_e32 v2, 0
	v_lshl_add_u64 v[150:151], s[36:37], 2, v[140:141]
	s_addc_u32 s25, s27, 0
	s_mov_b32 s64, -2
	v_mov_b64_e32 v[2:3], 0
	v_mov_b64_e32 v[4:5], 0
	v_mov_b64_e32 v[6:7], 0
	v_mov_b64_e32 v[8:9], 0
	v_mov_b64_e32 v[10:11], 0
	v_mov_b64_e32 v[12:13], 0
	v_mov_b64_e32 v[14:15], 0
	v_mov_b64_e32 v[16:17], 0
	v_mov_b64_e32 v[18:19], 0
	v_mov_b64_e32 v[20:21], 0
	v_mov_b64_e32 v[22:23], 0
	v_mov_b64_e32 v[24:25], 0
	v_mov_b64_e32 v[26:27], 0
	v_mov_b64_e32 v[28:29], 0
	v_mov_b64_e32 v[30:31], 0
	v_mov_b64_e32 v[32:33], 0
	v_mov_b64_e32 v[34:35], 0
	v_mov_b64_e32 v[36:37], 0
	v_mov_b64_e32 v[38:39], 0
	v_mov_b64_e32 v[40:41], 0
	v_mov_b64_e32 v[42:43], 0
	v_mov_b64_e32 v[44:45], 0
	v_mov_b64_e32 v[46:47], 0
	v_mov_b64_e32 v[48:49], 0
	v_mov_b64_e32 v[50:51], 0
	v_mov_b64_e32 v[52:53], 0
	v_mov_b64_e32 v[54:55], 0
	v_mov_b64_e32 v[56:57], 0
	v_mov_b64_e32 v[58:59], 0
	v_mov_b64_e32 v[60:61], 0
	v_mov_b64_e32 v[62:63], 0
	v_mov_b64_e32 v[64:65], 0
	v_mov_b64_e32 v[66:67], 0
	v_mov_b64_e32 v[68:69], 0
	v_mov_b64_e32 v[70:71], 0
	v_mov_b64_e32 v[72:73], 0
	v_mov_b64_e32 v[74:75], 0
	v_mov_b64_e32 v[76:77], 0
	v_mov_b64_e32 v[78:79], 0
	v_mov_b64_e32 v[80:81], 0
	v_mov_b64_e32 v[82:83], 0
	v_mov_b64_e32 v[84:85], 0
	v_mov_b64_e32 v[86:87], 0
	v_mov_b64_e32 v[88:89], 0
	v_mov_b64_e32 v[90:91], 0
	v_mov_b64_e32 v[92:93], 0
	v_mov_b64_e32 v[94:95], 0
	v_mov_b64_e32 v[96:97], 0
	v_mov_b64_e32 v[98:99], 0
	v_mov_b64_e32 v[100:101], 0
	v_mov_b64_e32 v[102:103], 0
	v_mov_b64_e32 v[104:105], 0
	v_mov_b64_e32 v[106:107], 0
	v_mov_b64_e32 v[108:109], 0
	v_mov_b64_e32 v[110:111], 0
	v_mov_b64_e32 v[112:113], 0
	v_mov_b64_e32 v[114:115], 0
	v_mov_b64_e32 v[116:117], 0
	v_mov_b64_e32 v[118:119], 0
	v_mov_b64_e32 v[120:121], 0
	v_mov_b64_e32 v[122:123], 0
	v_mov_b64_e32 v[124:125], 0
	v_mov_b64_e32 v[126:127], 0
	v_mov_b64_e32 v[128:129], 0
	s_branch .LBB0_693

; template <class Epi, class Sched, bool ALIGN_EPI = false, bool SP2 = false>
; __device__ __forceinline__ void gemm_phase(PG8_LAS unsigned char* lds, const Gemm g, const Sched& S, const Epi& E) {
;     ...
;             const bool last = (t == nt - 2);
;             const char* a1 = cA + (size_t)(t + 1) * kstep;
;             const char* a2 = last ? nA : cA + (size_t)(t + 2) * kstep; const char* b2 = last ? nB : cB + (size_t)(t + 2) * kstep;
;             const char* a3 = a2 + kstep; const char* b3 = b2 + kstep;
;     ...
;         for (int a = 0; a < 2; ++a)
; #pragma unroll
;             for (int b = 0; b < 2; ++b)
; #pragma unroll
;                 for (int m = 0; m < 4; ++m)
; #pragma unroll
;                     for (int n = 0; n < 2; ++n) acc[a][b][m][n] = (f32x4){0.f, 0.f, 0.f, 0.f};
.LBB0_790:
	s_add_u32 s51, s24, 0x100
	s_addc_u32 s52, s25, 0
	s_add_u32 s24, s26, 0x160080
	v_mov_b32_e32 v0, 0
	s_addc_u32 s25, s27, 0
	s_mov_b32 s53, -2
	v_mov_b64_e32 v[0:1], 0
	v_mov_b64_e32 v[2:3], 0
	v_mov_b64_e32 v[4:5], 0
	v_mov_b64_e32 v[6:7], 0
	v_mov_b64_e32 v[8:9], 0
	v_mov_b64_e32 v[10:11], 0
	v_mov_b64_e32 v[12:13], 0
	v_mov_b64_e32 v[14:15], 0
	v_mov_b64_e32 v[16:17], 0
	v_mov_b64_e32 v[18:19], 0
	v_mov_b64_e32 v[20:21], 0
	v_mov_b64_e32 v[22:23], 0
	v_mov_b64_e32 v[24:25], 0
	v_mov_b64_e32 v[26:27], 0
	v_mov_b64_e32 v[28:29], 0
	v_mov_b64_e32 v[30:31], 0
	v_mov_b64_e32 v[32:33], 0
	v_mov_b64_e32 v[34:35], 0
	v_mov_b64_e32 v[36:37], 0
	v_mov_b64_e32 v[38:39], 0
	v_mov_b64_e32 v[40:41], 0
	v_mov_b64_e32 v[42:43], 0
	v_mov_b64_e32 v[44:45], 0
	v_mov_b64_e32 v[46:47], 0
	v_mov_b64_e32 v[48:49], 0
	v_mov_b64_e32 v[50:51], 0
	v_mov_b64_e32 v[52:53], 0
	v_mov_b64_e32 v[54:55], 0
	v_mov_b64_e32 v[56:57], 0
	v_mov_b64_e32 v[58:59], 0
	v_mov_b64_e32 v[60:61], 0
	v_mov_b64_e32 v[62:63], 0
	v_mov_b64_e32 v[64:65], 0
	v_mov_b64_e32 v[66:67], 0
	v_mov_b64_e32 v[68:69], 0
	v_mov_b64_e32 v[70:71], 0
	v_mov_b64_e32 v[72:73], 0
	v_mov_b64_e32 v[74:75], 0
	v_mov_b64_e32 v[76:77], 0
	v_mov_b64_e32 v[78:79], 0
	v_mov_b64_e32 v[80:81], 0
	v_mov_b64_e32 v[82:83], 0
	v_mov_b64_e32 v[84:85], 0
	v_mov_b64_e32 v[86:87], 0
	v_mov_b64_e32 v[88:89], 0
	v_mov_b64_e32 v[90:91], 0
	v_mov_b64_e32 v[92:93], 0
	v_mov_b64_e32 v[94:95], 0
	v_mov_b64_e32 v[96:97], 0
	v_mov_b64_e32 v[98:99], 0
	v_mov_b64_e32 v[100:101], 0
	v_mov_b64_e32 v[102:103], 0
	v_mov_b64_e32 v[104:105], 0
	v_mov_b64_e32 v[106:107], 0
	v_mov_b64_e32 v[108:109], 0
	v_mov_b64_e32 v[110:111], 0
	v_mov_b64_e32 v[112:113], 0
	v_mov_b64_e32 v[114:115], 0
	v_mov_b64_e32 v[116:117], 0
	v_mov_b64_e32 v[118:119], 0
	v_mov_b64_e32 v[120:121], 0
	v_mov_b64_e32 v[122:123], 0
	v_mov_b64_e32 v[124:125], 0
	v_mov_b64_e32 v[126:127], 0
